# dropped the conservative vmcnt(0) at the start of each SWA head (previous head's store acks)
# speedup vs baseline: 1.0141x; 1.0014x over previous
; #define LAS __attribute__((address_space(3)))
; DI void swa_wg_unit(bf16_t* act, int b, int hk, int Qb, const float* sinks_l, LAS const float* tabS, LAS unsigned char* lds, int wid, int lane) {
;     ...
;     for (int g = 0; g < 4; ++g) {
;         const int hq = 4 * hk + g;
;         LAS const float* tab = tabS + hq * 128;
;         bf16x8 qf[4]; load_q(qf, act + rowq * PITCH + C_QC + hq * 64, h);
;         f32x16 o0, o1;
; #pragma unroll
;         for (int i = 0; i < 16; ++i) { o0[i] = 0.f; o1[i] = 0.f; }
;         float m = sinks_l[hq] * LOG2E, l = (h == 0) ? 1.0f : 0.f;
;         for (int t = tlo; t <= (q0 >> 6); ++t) {
.LBB0_378:
	s_add_i32 s10, s13, s14
	s_lshl_b32 s38, s10, 7
	v_lshl_add_u64 v[104:105], v[102:103], 0, s[38:39]
	v_mov_b32_e32 v31, 0
	s_andn2_b64 vcc, exec, s[8:9]
	v_mov_b32_e32 v30, 0
	v_mov_b32_e32 v29, 0
	v_mov_b32_e32 v28, 0
	v_mov_b32_e32 v27, 0
	v_mov_b32_e32 v26, 0
	v_mov_b32_e32 v25, 0
	v_mov_b32_e32 v24, 0
	v_mov_b32_e32 v23, 0
	v_mov_b32_e32 v22, 0
	v_mov_b32_e32 v21, 0
	v_mov_b32_e32 v20, 0
	v_mov_b32_e32 v19, 0
	v_mov_b32_e32 v18, 0
	v_mov_b32_e32 v17, 0
	v_mov_b32_e32 v16, 0
	v_mov_b32_e32 v47, 0
	v_mov_b32_e32 v46, 0
	v_mov_b32_e32 v45, 0
	v_mov_b32_e32 v44, 0
	v_mov_b32_e32 v43, 0
	v_mov_b32_e32 v42, 0
	v_mov_b32_e32 v41, 0
	v_mov_b32_e32 v40, 0
	v_mov_b32_e32 v39, 0
	v_mov_b32_e32 v38, 0
	v_mov_b32_e32 v37, 0
	v_mov_b32_e32 v36, 0
	v_mov_b32_e32 v35, 0
	v_mov_b32_e32 v34, 0
	v_mov_b32_e32 v33, 0
	v_mov_b32_e32 v32, 0
	v_lshl_add_u64 v[142:143], v[100:101], 0, s[38:39]
	global_load_dwordx2 v[160:161], v[142:143], off
	global_load_dwordx2 v[162:163], v[142:143], off offset:16
	global_load_dwordx2 v[164:165], v[142:143], off offset:32
	global_load_dwordx2 v[166:167], v[142:143], off offset:48
	global_load_dwordx2 v[168:169], v[142:143], off offset:64
	global_load_dwordx2 v[170:171], v[142:143], off offset:80
	global_load_dwordx2 v[172:173], v[142:143], off offset:96
	global_load_dwordx2 v[174:175], v[142:143], off offset:112
	v_mov_b32_e32 v118, v108
	s_cbranch_vccnz .LBB0_377
	s_lshl_b32 s11, s10, 9
	s_add_i32 s24, s11, 0
	s_mov_b32 s11, s39
	s_add_i32 s24, s24, 0x21080
	s_lshl_b64 s[26:27], s[10:11], 2
	s_add_u32 s26, s16, s26
	s_addc_u32 s27, s17, s27
	global_load_dwordx4 v[80:83], v[104:105], off
	global_load_dwordx4 v[84:87], v[104:105], off offset:32
	global_load_dword v32, v1, s[26:27]
	global_load_dwordx4 v[88:91], v[104:105], off offset:64
	global_load_dwordx4 v[92:95], v[104:105], off offset:96
	v_mov_b32_e32 v14, v1
	v_mov_b32_e32 v15, v1
	v_mov_b32_e32 v0, v1
	v_mov_b32_e32 v2, v1
	v_mov_b32_e32 v3, v1
	v_mov_b32_e32 v4, v1
	v_mov_b32_e32 v5, v1
	v_mov_b32_e32 v6, v1
	v_mov_b32_e32 v7, v1
	v_mov_b32_e32 v8, v1
	v_mov_b32_e32 v9, v1
	v_mov_b32_e32 v10, v1
	v_mov_b32_e32 v11, v1
	v_mov_b32_e32 v12, v1
	v_mov_b32_e32 v13, v1
	v_mov_b64_e32 v[30:31], v[14:15]
	v_mov_b32_e32 v119, v117
	v_mov_b32_e32 v120, v99
	s_mov_b32 s11, s23
	v_mov_b32_e32 v121, v97
	v_mov_b32_e32 v118, v108
	v_mov_b64_e32 v[28:29], v[12:13]
	v_mov_b64_e32 v[26:27], v[10:11]
	v_mov_b64_e32 v[24:25], v[8:9]
	v_mov_b64_e32 v[22:23], v[6:7]
	v_mov_b64_e32 v[20:21], v[4:5]
	v_mov_b64_e32 v[18:19], v[2:3]
	v_mov_b64_e32 v[16:17], v[0:1]
	s_waitcnt vmcnt(2)
	v_mul_f32_e32 v122, 0x3fb8aa3b, v32
	v_mov_b64_e32 v[46:47], v[14:15]
	v_mov_b64_e32 v[44:45], v[12:13]
	v_mov_b64_e32 v[42:43], v[10:11]
	v_mov_b64_e32 v[40:41], v[8:9]
	v_mov_b64_e32 v[38:39], v[6:7]
	v_mov_b64_e32 v[36:37], v[4:5]
	v_mov_b64_e32 v[34:35], v[2:3]
	v_mov_b64_e32 v[32:33], v[0:1]
	s_branch .LBB0_381
